# baseline (speedup 1.0000x reference)
.LBB0_331:
	s_cbranch_execz .LBB0_249
	v_readlane_b32 s34, v252, 16
	v_readlane_b32 s35, v252, 17
	s_cmp_lt_i32 s35, 2
	s_cbranch_scc1 .LBB0_371
	s_waitcnt vmcnt(0)
	v_cmp_eq_u32_e32 vcc, 0, v1
	s_waitcnt vmcnt(0)
	s_barrier
	s_and_saveexec_b64 s[0:1], vcc
	s_cbranch_execz .LBB0_370
	s_cmp_lg_u32 s101, 0
	s_cbranch_scc1 .Lxl_glob_1
	s_and_b32 s6, s2, 7
	v_mov_b32_e32 v2, 0
	v_mov_b32_e32 v3, 1
	s_nop 3
	s_lshl_b32 s3, s6, 8
	s_add_u32 s4, s86, s3
	s_addc_u32 s5, s87, 0
	s_add_u32 s4, s4, 0x2b00480
	s_addc_u32 s5, s5, 0
	s_mov_b32 s98, 0
	global_atomic_add v3, v2, v3, s[4:5] sc0
	s_waitcnt vmcnt(0)
	v_add_u32_e32 v3, 1, v3
	v_cmp_gt_u32_e32 vcc, s100, v3
	s_cbranch_vccz .Lxl_exit_1

.LBB0_496:
	s_cbranch_execz .LBB0_484
	v_readlane_b32 s34, v252, 16
	v_readlane_b32 s35, v252, 17
	s_cmp_lt_i32 s35, 4
	s_cbranch_scc1 .LBB0_536
	s_waitcnt vmcnt(0)
	v_cmp_eq_u32_e32 vcc, 0, v1
	s_waitcnt vmcnt(0)
	s_barrier
	s_and_saveexec_b64 s[0:1], vcc
	s_cbranch_execz .LBB0_535
	s_cmp_lg_u32 s101, 0
	s_cbranch_scc1 .Lxl_glob_3
	s_and_b32 s6, s2, 7
	v_mov_b32_e32 v2, 0
	v_mov_b32_e32 v3, 1
	s_nop 3
	s_lshl_b32 s3, s6, 8
	s_add_u32 s4, s86, s3
	s_addc_u32 s5, s87, 0
	s_add_u32 s4, s4, 0x2b00498
	s_addc_u32 s5, s5, 0
	s_mov_b32 s98, 0
	global_atomic_add v3, v2, v3, s[4:5] sc0
	s_waitcnt vmcnt(0)
	v_add_u32_e32 v3, 1, v3
	v_cmp_gt_u32_e32 vcc, s100, v3
	s_cbranch_vccz .Lxl_exit_3

.LBB0_550:
	s_cbranch_execz .LBB0_539
	v_readlane_b32 s34, v252, 16
	v_readlane_b32 s35, v252, 17
	s_cmp_lt_i32 s35, 5
	s_cbranch_scc1 .LBB0_590
	s_waitcnt vmcnt(0)
	v_cmp_eq_u32_e32 vcc, 0, v1
	s_waitcnt vmcnt(0)
	s_barrier
	s_and_saveexec_b64 s[0:1], vcc
	s_cbranch_execz .LBB0_589
	s_cmp_lg_u32 s101, 0
	s_cbranch_scc1 .Lxl_glob_4
	s_and_b32 s6, s2, 7
	v_mov_b32_e32 v2, 0
	v_mov_b32_e32 v3, 1
	s_nop 3
	s_lshl_b32 s3, s6, 8
	s_add_u32 s4, s86, s3
	s_addc_u32 s5, s87, 0
	s_add_u32 s4, s4, 0x2b00484
	s_addc_u32 s5, s5, 0
	s_mov_b32 s98, 0
	global_atomic_add v3, v2, v3, s[4:5] sc0
	s_waitcnt vmcnt(0)
	v_add_u32_e32 v3, 1, v3
	v_cmp_gt_u32_e32 vcc, s100, v3
	s_cbranch_vccz .Lxl_exit_4

.LBB0_620:
	s_cbranch_execz .LBB0_593
	v_readlane_b32 s34, v252, 16
	v_readlane_b32 s35, v252, 17
	s_cmp_lt_i32 s35, 6
	s_cbranch_scc1 .LBB0_660
	s_waitcnt vmcnt(0)
	v_cmp_eq_u32_e32 vcc, 0, v1
	s_waitcnt vmcnt(0) lgkmcnt(0)
	s_barrier
	s_and_saveexec_b64 s[0:1], vcc
	s_cbranch_execz .LBB0_659
	s_cmp_lg_u32 s101, 0
	s_cbranch_scc1 .Lxl_glob_5
	s_and_b32 s6, s2, 7
	v_mov_b32_e32 v2, 0
	v_mov_b32_e32 v3, 1
	s_nop 3
	s_lshl_b32 s3, s6, 8
	s_add_u32 s4, s86, s3
	s_addc_u32 s5, s87, 0
	s_add_u32 s4, s4, 0x2b00488
	s_addc_u32 s5, s5, 0
	s_mov_b32 s98, 0
	global_atomic_add v3, v2, v3, s[4:5] sc0
	s_waitcnt vmcnt(0)
	v_add_u32_e32 v3, 1, v3
	v_cmp_gt_u32_e32 vcc, s100, v3
	s_cbranch_vccz .Lxl_exit_5

.LBB0_669:
	v_readlane_b32 s34, v252, 16
	v_readlane_b32 s35, v252, 17
	s_cmp_lt_i32 s35, 7
	s_cbranch_scc1 .LBB0_708
	s_waitcnt vmcnt(0)
	v_cmp_eq_u32_e32 vcc, 0, v1
	s_waitcnt vmcnt(0)
	s_barrier
	s_and_saveexec_b64 s[0:1], vcc
	s_cbranch_execz .LBB0_707
	s_cmp_lg_u32 s101, 0
	s_cbranch_scc1 .Lxl_glob_6
	s_and_b32 s6, s2, 7
	v_mov_b32_e32 v2, 0
	v_mov_b32_e32 v3, 1
	s_nop 3
	s_lshl_b32 s3, s6, 8
	s_add_u32 s4, s86, s3
	s_addc_u32 s5, s87, 0
	s_add_u32 s4, s4, 0x2b0048c
	s_addc_u32 s5, s5, 0
	s_mov_b32 s98, 0
	global_atomic_add v3, v2, v3, s[4:5] sc0
	s_waitcnt vmcnt(0)
	v_add_u32_e32 v3, 1, v3
	v_cmp_gt_u32_e32 vcc, s100, v3
	s_cbranch_vccz .Lxl_exit_6

.LBB0_1027:
	v_readlane_b32 s34, v252, 16
	v_readlane_b32 s35, v252, 17
	s_cmp_lt_i32 s35, 10
	s_cbranch_scc1 .LBB0_1066
	s_waitcnt vmcnt(0)
	v_cmp_eq_u32_e32 vcc, 0, v1
	s_waitcnt vmcnt(0)
	s_barrier
	s_and_saveexec_b64 s[0:1], vcc
	s_cbranch_execz .LBB0_1065
	s_cmp_lg_u32 s101, 0
	s_cbranch_scc1 .Lxl_glob_9
	s_and_b32 s6, s2, 7
	v_mov_b32_e32 v2, 0
	v_mov_b32_e32 v3, 1
	s_nop 3
	s_lshl_b32 s3, s6, 8
	s_add_u32 s4, s86, s3
	s_addc_u32 s5, s87, 0
	s_add_u32 s4, s4, 0x2b0049c
	s_addc_u32 s5, s5, 0
	s_mov_b32 s98, 0
	global_atomic_add v3, v2, v3, s[4:5] sc0
	s_waitcnt vmcnt(0)
	v_add_u32_e32 v3, 1, v3
	v_cmp_gt_u32_e32 vcc, s100, v3
	s_cbranch_vccz .Lxl_exit_9

.LBB0_1104:
	s_cbranch_execz .LBB0_1070
	v_readlane_b32 s34, v252, 16
	v_readlane_b32 s35, v252, 17
	s_cmp_lt_i32 s35, 11
	s_cbranch_scc1 .LBB0_1144
	s_waitcnt vmcnt(0)
	v_cmp_eq_u32_e32 vcc, 0, v1
	s_waitcnt vmcnt(0) lgkmcnt(0)
	s_barrier
	s_and_saveexec_b64 s[0:1], vcc
	s_cbranch_execz .LBB0_1143
	s_cmp_lg_u32 s101, 0
	s_cbranch_scc1 .Lxl_glob_10
	s_and_b32 s6, s2, 7
	v_mov_b32_e32 v2, 0
	v_mov_b32_e32 v3, 1
	s_nop 3
	s_lshl_b32 s3, s6, 8
	s_add_u32 s4, s86, s3
	s_addc_u32 s5, s87, 0
	s_add_u32 s4, s4, 0x2b00490
	s_addc_u32 s5, s5, 0
	s_mov_b32 s98, 0
	global_atomic_add v3, v2, v3, s[4:5] sc0
	s_waitcnt vmcnt(0)
	v_add_u32_e32 v3, 1, v3
	v_cmp_gt_u32_e32 vcc, s100, v3
	s_cbranch_vccz .Lxl_exit_10

.LBB0_1153:
	v_readlane_b32 s34, v252, 16
	v_readlane_b32 s35, v252, 17
	s_cmp_lt_i32 s35, 12
	s_cbranch_scc1 .LBB0_1192
	s_waitcnt vmcnt(0)
	v_cmp_eq_u32_e32 vcc, 0, v1
	s_waitcnt vmcnt(0)
	s_barrier
	s_and_saveexec_b64 s[0:1], vcc
	s_cbranch_execz .LBB0_1191
	s_cmp_lg_u32 s101, 0
	s_cbranch_scc1 .Lxl_glob_11
	s_and_b32 s6, s2, 7
	v_mov_b32_e32 v2, 0
	v_mov_b32_e32 v3, 1
	s_nop 3
	s_lshl_b32 s3, s6, 8
	s_add_u32 s4, s86, s3
	s_addc_u32 s5, s87, 0
	s_add_u32 s4, s4, 0x2b00494
	s_addc_u32 s5, s5, 0
	s_mov_b32 s98, 0
	global_atomic_add v3, v2, v3, s[4:5] sc0
	s_waitcnt vmcnt(0)
	v_add_u32_e32 v3, 1, v3
	v_cmp_gt_u32_e32 vcc, s100, v3
	s_cbranch_vccz .Lxl_exit_11
